# FoX tile loop back-edge rotation: next-tile bookkeeping, address arithmetic and the tile-after-next global loads issued before the workgroup barrier instead of after it
# baseline (speedup 1.0000x reference)
.LBB0_171:
	s_and_b64 s[0:1], exec, s[56:57]
	s_cselect_b32 s7, -1, s13
	s_add_u32 s0, s52, -1
	s_addc_u32 s1, s53, -1
	s_and_b64 s[52:53], s[0:1], s[52:53]
	s_mov_b32 s13, s6
	s_and_b64 vcc, exec, s[48:49]
	s_cbranch_vccnz .Lfxr_od_brk
	s_cmp_eq_u64 s[52:53], 0
	s_cselect_b64 s[48:49], -1, 0
	s_cmp_lg_u64 s[52:53], 0
	s_cselect_b64 s[50:51], -1, 0
	s_ff1_i32_b64 s6, s[52:53]
	s_and_b64 vcc, exec, s[48:49]
	s_cbranch_vccnz .Lfxr_od_bar
	s_lshl_b32 s18, s6, 6
	v_add_u32_e32 v0, s18, v128
	v_min_i32_e32 v0, 0xfff, v0
	v_mad_i64_i32 v[2:3], s[0:1], v0, s23, v[120:121]
	v_lshlrev_b64 v[2:3], 1, v[2:3]
	v_lshl_add_u64 v[4:5], s[26:27], 0, v[2:3]
	v_lshl_add_u64 v[2:3], s[30:31], 0, v[2:3]
	global_load_dwordx4 v[6:9], v[4:5], off
	s_nop 0
	global_load_dwordx4 v[2:5], v[2:3], off
	v_and_b32_e32 v10, 63, v127
	v_add_u32_e32 v10, s18, v10
	v_ashrrev_i32_e32 v11, 31, v10
	v_lshl_add_u64 v[10:11], v[10:11], 2, s[42:43]
	global_load_dword v141, v[10:11], off
.Lfxr_od_bar:
	s_waitcnt lgkmcnt(0)
	s_barrier
	s_lshl_b32 s0, s13, 6
	v_cmp_le_i32_e32 vcc, s0, v133
	s_and_saveexec_b64 s[56:57], vcc
	s_cbranch_execnz .LBB0_178
	s_branch .LBB0_174
.Lfxr_od_brk:
	s_waitcnt lgkmcnt(0)
	s_barrier
	s_branch .LBB0_159

.LBB0_186:
	s_cmp_lt_i32 s7, 0
	s_cbranch_scc1 .Lfxr_ev_brk
	s_add_u32 s0, s52, -1
	s_addc_u32 s1, s53, -1
	s_and_b64 s[52:53], s[0:1], s[52:53]
	s_cmp_eq_u64 s[52:53], 0
	s_cselect_b64 s[56:57], -1, 0
	s_ff1_i32_b64 s13, s[52:53]
	s_and_b64 vcc, exec, s[56:57]
	s_cbranch_vccnz .Lfxr_ev_bar
	s_lshl_b32 s18, s13, 6
	v_add_u32_e32 v0, s18, v128
	v_min_i32_e32 v0, 0xfff, v0
	v_mad_i64_i32 v[10:11], s[0:1], v0, s23, v[120:121]
	v_lshlrev_b64 v[10:11], 1, v[10:11]
	v_lshl_add_u64 v[12:13], s[26:27], 0, v[10:11]
	v_lshl_add_u64 v[10:11], s[30:31], 0, v[10:11]
	global_load_dwordx4 v[112:115], v[12:13], off
	global_load_dwordx4 v[116:119], v[10:11], off
	v_and_b32_e32 v10, 63, v127
	v_add_u32_e32 v10, s18, v10
	v_ashrrev_i32_e32 v11, 31, v10
	v_lshl_add_u64 v[10:11], v[10:11], 2, s[42:43]
	global_load_dword v130, v[10:11], off
.Lfxr_ev_bar:
	s_waitcnt lgkmcnt(0)
	s_barrier
	s_lshl_b32 s0, s7, 6
	v_cmp_le_i32_e32 vcc, s0, v133
	s_and_saveexec_b64 s[58:59], vcc
	s_cbranch_execnz .LBB0_194

; __device__ __forceinline__ f32x16 mfma32(bf16x8 a, bf16x8 b, f32x16 c) { return __builtin_amdgcn_mfma_f32_32x32x16_bf16(a, b, c, 0, 0, 0); }
; template <int MODE> ...
;     ...
;         const lptr Kt = L + A_KT + buf * 9216, Vt = L + A_VT + vcur * 12288;
;         f32x16 s0, s1;
; #pragma unroll
;         for (int s4 = 0; s4 < 4; ++s4) {
;             const bf16x8 a0 = lds_ld<bf16x8>(Kt + n * KP + s4 * 32 + hl * 16);
;             const bf16x8 a1 = lds_ld<bf16x8>(Kt + (32 + n) * KP + s4 * 32 + hl * 16);
;             if (s4 == 0) { s0 = mfma32(a0, qf[0], negm); s1 = mfma32(a1, qf[0], negm); }
;             else { s0 = mfma32(a0, qf[s4], s0); s1 = mfma32(a1, qf[s4], s1); }
;         }
;         const int kbase = 64 * kt + 4 * hl;
;         const bool far = (MODE == MODE_WIN || MODE == MODE_SEL) ? (wtmin - (64 * kt + 63) >= 128) : false;
;         const bool fmask = (MODE == MODE_FOX) ? (64 * kt + 63 > wtmin) : false;
;         const bool clean = (MODE == MODE_WIN) ? (far && (wtmax - 64 * kt < W)) : false;
;         const float mref = (MODE == MODE_CMP2) ? mfix : ((m == -INFINITY) ? 0.f : m);
;         if (MODE == MODE_FOX) {
; #pragma unroll
;             for (int kb = 0; kb < 2; ++kb)
; #pragma unroll
;                 for (int a = 0; a < 4; ++a) {
;                     const f32x4 c4 = lds_ld<f32x4>(L + A_CB + buf * 256 + (32 * kb + 8 * a + 4 * hl) * 4);
; #pragma unroll
;                     for (int e = 0; e < 4; ++e) { const int r = 4 * a + e; if (kb) s1[r] = s1[r] * SC2 + c4[e]; else s0[r] = s0[r] * SC2 + c4[e]; }
;                 }
;             if (__builtin_amdgcn_readfirstlane((int)fmask)) {
; #pragma unroll
;                 for (int r = 0; r < 16; ++r) {
;                     const int key = kbase + 8 * (r >> 2) + (r & 3);
;                     if (key > t) s0[r] = -INFINITY;
;                     if (key + 32 > t) s1[r] = -INFINITY;
;                 }
;             }
.Lfxr_ev_brk:
	s_waitcnt lgkmcnt(0)
	s_barrier
.LBB0_190:
	s_mov_b32 s13, s6
	s_cbranch_execz .LBB0_172
	s_branch .LBB0_159
.LBB0_194:
	v_add_u32_e32 v14, v134, v135
	v_add_u32_e32 v0, v136, v135
	v_add_u32_e32 v156, v138, v139
	ds_read_b128 v[170:173], v14 offset:9216
	ds_read_b128 v[174:177], v0 offset:9216
	ds_read_b128 v[178:181], v14 offset:9248
	ds_read_b128 v[182:185], v0 offset:9248
	ds_read_b128 v[186:189], v14 offset:9280
	ds_read_b128 v[194:197], v0 offset:9280
	ds_read_b128 v[198:201], v14 offset:9312
	ds_read_b128 v[202:205], v0 offset:9312
	ds_read_b128 v[144:147], v135 offset:43264
	ds_read_b128 v[148:151], v135 offset:43296
	ds_read_b128 v[152:155], v135 offset:43328
	ds_read_b128 v[12:15], v135 offset:43360
	s_or_b32 s1, s0, 63
	v_cmp_gt_i32_e32 vcc, s1, v125
	s_waitcnt lgkmcnt(11)
	v_mfma_f32_32x32x16_bf16 v[80:95], v[170:173], v[104:107], v[48:63]
	ds_read_b64_tr_b16 v[206:207], v156 offset:30720
	ds_read_b64_tr_b16 v[208:209], v156 offset:32256
	s_waitcnt lgkmcnt(12)
	v_mfma_f32_32x32x16_bf16 v[64:79], v[174:177], v[104:107], v[48:63]
	ds_read_b64_tr_b16 v[210:211], v156 offset:33792
	ds_read_b64_tr_b16 v[212:213], v156 offset:35328
	s_waitcnt lgkmcnt(13)
	v_mfma_f32_32x32x16_bf16 v[80:95], v[178:181], v[96:99], v[80:95]
	ds_read_b64_tr_b16 v[226:227], v156 offset:36864
	ds_read_b64_tr_b16 v[228:229], v156 offset:38400
	s_waitcnt lgkmcnt(14)
	v_mfma_f32_32x32x16_bf16 v[64:79], v[182:185], v[96:99], v[64:79]
	ds_read_b64_tr_b16 v[230:231], v156 offset:39936
	ds_read_b64_tr_b16 v[232:233], v156 offset:41472
	ds_read_b128 v[170:173], v135 offset:43392
	ds_read_b128 v[174:177], v135 offset:43424
	ds_read_b128 v[178:181], v135 offset:43456
	ds_read_b128 v[182:185], v135 offset:43488
	s_waitcnt lgkmcnt(15)
	v_mfma_f32_32x32x16_bf16 v[80:95], v[186:189], v[100:103], v[80:95]
	ds_read_b64_tr_b16 v[234:235], v156 offset:30784
	ds_read_b64_tr_b16 v[236:237], v156 offset:32320
	s_waitcnt lgkmcnt(15)
	v_mfma_f32_32x32x16_bf16 v[64:79], v[194:197], v[100:103], v[64:79]
	ds_read_b64_tr_b16 v[238:239], v156 offset:33856
	ds_read_b64_tr_b16 v[240:241], v156 offset:35392
	v_cndmask_b32_e64 v0, 0, 1, vcc
	s_nop 0
	v_readfirstlane_b32 s1, v0
	s_bitcmp0_b32 s1, 0
	s_waitcnt lgkmcnt(15)
	v_mfma_f32_32x32x16_bf16 v[80:95], v[198:201], v[108:111], v[80:95]
	ds_read_b64_tr_b16 v[242:243], v156 offset:36928
	ds_read_b64_tr_b16 v[244:245], v156 offset:38464
	s_waitcnt lgkmcnt(15)
	v_mfma_f32_32x32x16_bf16 v[64:79], v[202:205], v[108:111], v[64:79]
	ds_read_b64_tr_b16 v[246:247], v156 offset:40000
	ds_read_b64_tr_b16 v[248:249], v156 offset:41536
	s_waitcnt lgkmcnt(15)
	s_nop 5
	v_fma_f32 v82, v82, s54, v146
	v_fma_f32 v83, v83, s54, v147
	v_fma_f32 v86, v86, s54, v150
	v_fma_f32 v87, v87, s54, v151
	v_fma_f32 v88, v88, s54, v152
	v_fma_f32 v89, v89, s54, v153
	v_fma_f32 v10, v94, s54, v14
	v_fma_f32 v11, v95, s54, v15
	v_fma_f32 v12, v92, s54, v12
	v_fma_f32 v13, v93, s54, v13
	v_fma_f32 v14, v90, s54, v154
	v_fma_f32 v15, v91, s54, v155
	v_fma_f32 v84, v84, s54, v148
	v_fma_f32 v85, v85, s54, v149
	v_fma_f32 v80, v80, s54, v144
	v_fma_f32 v81, v81, s54, v145
	s_waitcnt lgkmcnt(8)
	v_fma_f32 v66, v66, s54, v172
	v_fma_f32 v67, v67, s54, v173
	v_fma_f32 v70, v70, s54, v176
	v_fma_f32 v71, v71, s54, v177
	v_fma_f32 v74, v74, s54, v180
	v_fma_f32 v75, v75, s54, v181
	v_fma_f32 v78, v78, s54, v184
	v_fma_f32 v79, v79, s54, v185
	v_fma_f32 v76, v76, s54, v182
	v_fma_f32 v77, v77, s54, v183
	v_fma_f32 v72, v72, s54, v178
	v_fma_f32 v73, v73, s54, v179
	v_fma_f32 v68, v68, s54, v174
	v_fma_f32 v69, v69, s54, v175
	v_fma_f32 v64, v64, s54, v170
	v_fma_f32 v65, v65, s54, v171
	s_cbranch_scc1 .LBB0_196
	v_or_b32_e32 v0, s0, v137
	v_or_b32_e32 v90, 32, v0
	v_cmp_le_i32_e32 vcc, v90, v126
	v_or_b32_e32 v90, 33, v0
	s_nop 0
	v_cndmask_b32_e32 v64, v220, v64, vcc
	v_cmp_lt_i32_e32 vcc, v0, v126
	s_nop 1
	v_cndmask_b32_e32 v81, v220, v81, vcc
	v_cmp_le_i32_e32 vcc, v0, v126
	s_nop 1
	v_cndmask_b32_e32 v80, v220, v80, vcc
	v_cmp_le_i32_e32 vcc, v90, v126
	v_or_b32_e32 v90, 2, v0
	s_nop 0
	v_cndmask_b32_e32 v65, v220, v65, vcc
	v_cmp_le_i32_e32 vcc, v90, v126
	v_or_b32_e32 v90, 34, v0
	s_nop 0
	v_cndmask_b32_e32 v82, v220, v82, vcc
	v_cmp_le_i32_e32 vcc, v90, v126
	v_or_b32_e32 v90, 3, v0
	s_nop 0
	v_cndmask_b32_e32 v66, v220, v66, vcc
	v_cmp_le_i32_e32 vcc, v90, v126
	v_or_b32_e32 v90, 35, v0
	s_nop 0
	v_cndmask_b32_e32 v83, v220, v83, vcc
	v_cmp_le_i32_e32 vcc, v90, v126
	v_or_b32_e32 v90, 8, v0
	s_nop 0
	v_cndmask_b32_e32 v67, v220, v67, vcc
	v_cmp_le_i32_e32 vcc, v90, v126
	v_or_b32_e32 v90, 40, v0
	s_nop 0
	v_cndmask_b32_e32 v84, v220, v84, vcc
	v_cmp_le_i32_e32 vcc, v90, v126
	v_or_b32_e32 v90, 9, v0
	s_nop 0
	v_cndmask_b32_e32 v68, v220, v68, vcc
	v_cmp_le_i32_e32 vcc, v90, v126
	v_or_b32_e32 v90, 41, v0
	s_nop 0
	v_cndmask_b32_e32 v85, v220, v85, vcc
	v_cmp_le_i32_e32 vcc, v90, v126
	v_or_b32_e32 v90, 10, v0
	s_nop 0
	v_cndmask_b32_e32 v69, v220, v69, vcc
	v_cmp_le_i32_e32 vcc, v90, v126
	v_or_b32_e32 v90, 42, v0
	s_nop 0
	v_cndmask_b32_e32 v86, v220, v86, vcc
	v_cmp_le_i32_e32 vcc, v90, v126
	v_or_b32_e32 v90, 11, v0
	s_nop 0
	v_cndmask_b32_e32 v70, v220, v70, vcc
	v_cmp_le_i32_e32 vcc, v90, v126
	v_or_b32_e32 v90, 43, v0
	s_nop 0
	v_cndmask_b32_e32 v87, v220, v87, vcc
	v_cmp_le_i32_e32 vcc, v90, v126
	v_or_b32_e32 v90, 16, v0
	s_nop 0
	v_cndmask_b32_e32 v71, v220, v71, vcc
	v_cmp_le_i32_e32 vcc, v90, v126
	v_or_b32_e32 v90, 48, v0
	s_nop 0
	v_cndmask_b32_e32 v88, v220, v88, vcc
	v_cmp_le_i32_e32 vcc, v90, v126
	v_or_b32_e32 v90, 17, v0
	s_nop 0
	v_cndmask_b32_e32 v72, v220, v72, vcc
	v_cmp_le_i32_e32 vcc, v90, v126
	v_or_b32_e32 v90, 49, v0
	s_nop 0
	v_cndmask_b32_e32 v89, v220, v89, vcc
	v_cmp_le_i32_e32 vcc, v90, v126
	v_or_b32_e32 v90, 18, v0
	s_nop 0
	v_cndmask_b32_e32 v73, v220, v73, vcc
	v_cmp_le_i32_e32 vcc, v90, v126
	v_or_b32_e32 v90, 50, v0
	s_nop 0
	v_cndmask_b32_e32 v14, v220, v14, vcc
	v_cmp_le_i32_e32 vcc, v90, v126
	v_or_b32_e32 v90, 19, v0
	s_nop 0
	v_cndmask_b32_e32 v74, v220, v74, vcc
	v_cmp_le_i32_e32 vcc, v90, v126
	v_or_b32_e32 v90, 51, v0
	s_nop 0
	v_cndmask_b32_e32 v15, v220, v15, vcc
	v_cmp_le_i32_e32 vcc, v90, v126
	v_or_b32_e32 v90, 24, v0
	s_nop 0
	v_cndmask_b32_e32 v75, v220, v75, vcc
	v_cmp_le_i32_e32 vcc, v90, v126
	v_or_b32_e32 v90, 56, v0
	s_nop 0
	v_cndmask_b32_e32 v12, v220, v12, vcc
	v_cmp_le_i32_e32 vcc, v90, v126
	v_or_b32_e32 v90, 25, v0
	s_nop 0
	v_cndmask_b32_e32 v76, v220, v76, vcc
	v_cmp_le_i32_e32 vcc, v90, v126
	v_or_b32_e32 v90, 57, v0
	s_nop 0
	v_cndmask_b32_e32 v13, v220, v13, vcc
	v_cmp_le_i32_e32 vcc, v90, v126
	v_or_b32_e32 v90, 26, v0
	s_nop 0
	v_cndmask_b32_e32 v77, v220, v77, vcc
	v_cmp_le_i32_e32 vcc, v90, v126
	v_or_b32_e32 v90, 58, v0
	s_nop 0
	v_cndmask_b32_e32 v10, v220, v10, vcc
	v_cmp_le_i32_e32 vcc, v90, v126
	v_or_b32_e32 v90, 27, v0
	v_or_b32_e32 v0, 59, v0
	v_cndmask_b32_e32 v78, v220, v78, vcc
	v_cmp_le_i32_e32 vcc, v90, v126
	s_nop 1
	v_cndmask_b32_e32 v11, v220, v11, vcc
	v_cmp_le_i32_e32 vcc, v0, v126
	s_nop 1
	v_cndmask_b32_e32 v79, v220, v79, vcc
